# mixer work queue: next ticket fetched at item start; the loop top uses a counted wait (no store drain, no atomic round trip)
# baseline (speedup 1.0000x reference)
.Lsb_wB_x:
	s_or_b64 exec, exec, s[100:101]
	v_mov_b32_e32 v245, 0xc0135761
	s_barrier
	v_writelane_b32 v242, s10, 48
	s_and_b64 s[0:1], s[10:11], exec
	s_cselect_b32 s87, 0, 4
	s_lshl_b32 s92, s96, 1
	s_xor_b32 s91, s87, 0x104
	s_lshl_b64 s[0:1], s[92:93], 2
	v_readlane_b32 s4, v243, 24
	s_add_u32 s46, s4, s0
	v_readlane_b32 s0, v243, 25
	s_addc_u32 s47, s0, s1
	s_lshl_b32 s0, s87, 1
	v_writelane_b32 v242, s11, 49
	s_addk_i32 s0, 0xfefc
	v_writelane_b32 v242, s0, 51
	s_mul_i32 s92, s96, 0x3e00
	v_readlane_b32 s4, v242, 32
	s_lshl_b32 s97, s91, 1
	s_cmp_eq_u32 s87, 0
	s_cselect_b32 s98, 8, 0
	s_add_i32 s97, s97, s98
	s_lshl_b64 s[0:1], s[92:93], 2
	v_readlane_b32 s6, v242, 34
	v_readlane_b32 s7, v242, 35
	s_add_u32 s50, s6, s0
	v_readlane_b32 s5, v242, 33
	s_addc_u32 s51, s7, s1
	s_lshl_b32 s52, s96, 9
	s_mov_b32 s53, s93
	v_readlane_b32 s10, v242, 38
	s_lshl_b64 s[4:5], s[52:53], 2
	v_readlane_b32 s11, v242, 39
	s_add_u32 s54, s10, s4
	s_addc_u32 s55, s11, s5
	v_readlane_b32 s12, v242, 26
	v_readlane_b32 s13, v242, 27
	s_add_u32 s58, s12, s4
	v_readlane_b32 s14, v242, 28
	s_addc_u32 s59, s13, s5
	s_lshl_b32 s53, s96, 3
	v_readlane_b32 s15, v242, 29
	s_add_u32 s0, s14, s4
	s_addc_u32 s1, s15, s5
	v_readlane_b32 s6, v242, 24
	v_readlane_b32 s7, v242, 25
	s_add_u32 s72, s6, s4
	s_addc_u32 s73, s7, s5
	v_readlane_b32 s8, v242, 36
	v_readlane_b32 s9, v242, 37
	s_and_saveexec_b64 s[100:101], s[56:57]
	v_mov_b32_e32 v247, 1
	global_atomic_add v247, v145, v247, s[46:47] sc0
	s_or_b64 exec, exec, s[100:101]
	s_waitcnt vmcnt(0)
	s_branch .LBB0_364

.LBB0_364:
	s_barrier
	s_and_saveexec_b64 s[40:41], s[56:57]
	s_cbranch_execz .LBB0_368
	s_waitcnt vmcnt(16)
	v_readfirstlane_b32 s4, v247
	v_mov_b32_e32 v1, s33
	s_nop 0
	v_mov_b32_e32 v0, s4
	ds_write_b32 v1, v0
.LBB0_368:
	s_or_b64 exec, exec, s[40:41]
	v_mov_b32_e32 v0, s33
	s_waitcnt lgkmcnt(0)
	s_barrier
	ds_read_b32 v0, v0
	s_waitcnt lgkmcnt(0)
	v_cmp_le_i32_e64 s[40:41], s97, v0
	v_readfirstlane_b32 s92, v0
	s_and_b64 vcc, exec, s[40:41]
	s_cbranch_vccnz .LBB0_363
	s_and_saveexec_b64 s[100:101], s[56:57]
	v_mov_b32_e32 v247, 1
	global_atomic_add v247, v145, v247, s[46:47] sc0
	s_or_b64 exec, exec, s[100:101]
	s_cmp_ge_i32 s92, s91
	s_mov_b64 s[42:43], -1
	s_cbranch_scc0 .LBB0_397
	v_mov_b32_e32 v108, v175
	s_movk_i32 s5, 0x3000
	v_ashrrev_i32_e32 v109, 31, v108
	v_lshl_add_u64 v[0:1], v[108:109], 2, s[50:51]
	v_add_co_u32_e32 v2, vcc, s74, v0
	s_mov_b64 s[44:45], s[68:69]
	s_nop 0
	v_addc_co_u32_e32 v3, vcc, 0, v1, vcc
	v_add_co_u32_e32 v4, vcc, s3, v0
	v_readlane_b32 s4, v242, 51
	s_nop 0
	v_addc_co_u32_e32 v5, vcc, 0, v1, vcc
	v_add_co_u32_e32 v6, vcc, s5, v0
	s_movk_i32 s5, 0x4000
	s_nop 0
	v_addc_co_u32_e32 v7, vcc, 0, v1, vcc
	v_add_co_u32_e32 v8, vcc, s5, v0
	s_movk_i32 s5, 0x5000
	s_nop 0
	v_addc_co_u32_e32 v9, vcc, 0, v1, vcc
	v_add_co_u32_e32 v10, vcc, s5, v0
	s_movk_i32 s5, 0x6000
	s_nop 0
	v_addc_co_u32_e32 v11, vcc, 0, v1, vcc
	v_add_co_u32_e32 v12, vcc, s5, v0
	s_movk_i32 s5, 0x7000
	s_nop 0
	v_addc_co_u32_e32 v13, vcc, 0, v1, vcc
	global_load_dword v109, v[4:5], off offset:-4096
	global_load_dword v110, v[4:5], off
	global_load_dword v111, v[4:5], off offset:2048
	global_load_dword v112, v[8:9], off offset:-4096
	global_load_dword v113, v[8:9], off
	global_load_dword v114, v[8:9], off offset:2048
	global_load_dword v115, v[12:13], off offset:-4096
	global_load_dword v116, v[12:13], off
	v_add_co_u32_e32 v4, vcc, s5, v0
	s_mov_b32 s5, 0x8000
	s_nop 0
	v_addc_co_u32_e32 v5, vcc, 0, v1, vcc
	v_add_co_u32_e32 v8, vcc, s5, v0
	s_mov_b32 s5, 0x9000
	s_nop 0
	v_addc_co_u32_e32 v9, vcc, 0, v1, vcc
	v_add_co_u32_e32 v14, vcc, s5, v0
	s_mov_b32 s5, 0xa000
	s_nop 0
	v_addc_co_u32_e32 v15, vcc, 0, v1, vcc
	v_add_co_u32_e32 v16, vcc, s5, v0
	s_mov_b32 s5, 0xb000
	s_nop 0
	v_addc_co_u32_e32 v17, vcc, 0, v1, vcc
	v_add_co_u32_e32 v18, vcc, s5, v0
	s_mov_b32 s5, 0xc000
	s_nop 0
	v_addc_co_u32_e32 v19, vcc, 0, v1, vcc
	v_add_co_u32_e32 v20, vcc, s5, v0
	s_mov_b32 s5, 0xd000
	s_nop 0
	v_addc_co_u32_e32 v21, vcc, 0, v1, vcc
	global_load_dword v117, v[12:13], off offset:2048
	global_load_dword v118, v[8:9], off offset:-4096
	global_load_dword v119, v[8:9], off
	global_load_dword v120, v[8:9], off offset:2048
	global_load_dword v121, v[16:17], off offset:-4096
	global_load_dword v122, v[16:17], off
	global_load_dword v123, v[16:17], off offset:2048
	global_load_dword v124, v[20:21], off offset:-4096
	global_load_dword v125, v[0:1], off
	global_load_dword v126, v[0:1], off offset:2048
	global_load_dword v127, v[2:3], off offset:2048
	global_load_dword v128, v[6:7], off offset:2048
	global_load_dword v129, v[10:11], off offset:2048
	global_load_dword v130, v[4:5], off offset:2048
	global_load_dword v131, v[14:15], off offset:2048
	global_load_dword v132, v[18:19], off offset:2048
	v_add_co_u32_e32 v2, vcc, s5, v0
	s_mov_b32 s5, 0xe000
	s_nop 0
	v_addc_co_u32_e32 v3, vcc, 0, v1, vcc
	s_add_i32 s4, s4, s92
	v_add_co_u32_e32 v4, vcc, s5, v0
	s_add_u32 s48, s44, 0x7900000
	s_nop 0
	v_addc_co_u32_e32 v5, vcc, 0, v1, vcc
	s_mov_b32 s5, 0xf000
	s_addc_u32 s49, s45, 0
	s_lshl_b32 s82, s4, 6
	s_cmpk_ge_i32 s4, 0xfc
	s_cselect_b32 s98, 1, 0
	s_cmp_eq_u32 s87, 0
	s_cselect_b32 s99, 1, 0
	s_and_b32 s98, s98, s99
	s_add_i32 s99, s4, 0xfc
	s_lshl_b32 s99, s99, 5
	s_cmp_lg_u32 s98, 0
	s_cselect_b32 s82, s99, s82
	v_add_co_u32_e32 v0, vcc, s5, v0
	s_cmp_lt_i32 s4, 4
	global_load_dword v133, v[20:21], off
	global_load_dword v134, v[20:21], off offset:2048
	global_load_dword v135, v[4:5], off offset:-4096
	global_load_dword v136, v[4:5], off
	global_load_dword v137, v[4:5], off offset:2048
	v_addc_co_u32_e32 v1, vcc, 0, v1, vcc
	global_load_dword v138, v[2:3], off offset:2048
	global_load_dword v139, v[0:1], off
	v_add_u32_e32 v0, s52, v108
	v_readlane_b32 s8, v242, 32
	v_ashrrev_i32_e32 v142, 6, v108
	s_cselect_b32 s4, 0, 0x100
	v_ashrrev_i32_e32 v1, 31, v0
	v_readlane_b32 s12, v242, 36
	v_readlane_b32 s13, v242, 37
	s_cselect_b32 s5, 0x100, s31
	s_add_i32 s6, s82, -15
	v_min_i32_e32 v16, 0x5d, v142
	v_lshl_add_u64 v[0:1], v[0:1], 2, s[12:13]
	s_add_i32 s7, s5, -1
	v_add_u32_e32 v16, s6, v16
	global_load_dword v140, v[0:1], off
	v_lshlrev_b32_e32 v0, 3, v108
	v_min_i32_e32 v17, s7, v16
	v_mov_b32_e32 v20, s4
	v_cmp_gt_i32_e32 vcc, s4, v16
	v_readlane_b32 s9, v242, 33
	v_and_b32_e32 v141, 0x1f8, v0
	v_cndmask_b32_e32 v18, v17, v20, vcc
	v_mov_b64_e32 v[16:17], s[48:49]
	v_mad_u64_u32 v[18:19], s[8:9], v18, s62, v[16:17]
	v_lshlrev_b32_e32 v144, 1, v141
	v_lshl_add_u64 v[18:19], v[18:19], 0, v[144:145]
	v_add_co_u32_e32 v18, vcc, s74, v18
	v_lshlrev_b32_e32 v12, 2, v141
	s_nop 0
	v_addc_co_u32_e32 v19, vcc, 0, v19, vcc
	global_load_dwordx4 v[0:3], v12, s[54:55] offset:16
	global_load_dwordx4 v[4:7], v12, s[54:55]
	global_load_dwordx4 v[8:11], v12, s[58:59] offset:16
	s_nop 0
	global_load_dwordx4 v[12:15], v12, s[58:59]
	s_barrier
	global_load_dwordx4 v[104:107], v[18:19], off
	global_load_dwordx4 v[168:171], v[18:19], off offset:1024
	v_add_u32_e32 v18, 0x200, v108
	v_ashrrev_i32_e32 v166, 6, v18
	v_min_i32_e32 v18, 0x5d, v166
	v_add_u32_e32 v18, s6, v18
	v_min_i32_e32 v19, s7, v18
	v_cmp_gt_i32_e32 vcc, s4, v18
	v_readlane_b32 s10, v242, 34
	v_readlane_b32 s11, v242, 35
	v_cndmask_b32_e32 v18, v19, v20, vcc
	v_mad_u64_u32 v[18:19], s[8:9], v18, s62, v[16:17]
	v_lshl_add_u64 v[18:19], v[18:19], 0, v[144:145]
	v_add_co_u32_e32 v18, vcc, s74, v18
	v_readlane_b32 s14, v242, 38
	s_nop 0
	v_addc_co_u32_e32 v19, vcc, 0, v19, vcc
	global_load_dwordx4 v[96:99], v[18:19], off
	global_load_dwordx4 v[100:103], v[18:19], off offset:1024
	v_add_u32_e32 v18, 0x400, v108
	v_ashrrev_i32_e32 v165, 6, v18
	v_min_i32_e32 v18, 0x5d, v165
	v_add_u32_e32 v18, s6, v18
	v_min_i32_e32 v19, s7, v18
	v_cmp_gt_i32_e32 vcc, s4, v18
	v_readlane_b32 s15, v242, 39
	s_waitcnt vmcnt(3)
	v_lshlrev_b32_e32 v172, 16, v104
	v_cndmask_b32_e32 v18, v19, v20, vcc
	v_mad_u64_u32 v[18:19], s[8:9], v18, s62, v[16:17]
	v_lshl_add_u64 v[18:19], v[18:19], 0, v[144:145]
	v_add_co_u32_e32 v18, vcc, s74, v18
	s_waitcnt vmcnt(2)
	v_lshlrev_b32_e32 v156, 16, v168
	v_addc_co_u32_e32 v19, vcc, 0, v19, vcc
	global_load_dwordx4 v[88:91], v[18:19], off
	global_load_dwordx4 v[92:95], v[18:19], off offset:1024
	v_add_u32_e32 v18, 0x600, v108
	v_ashrrev_i32_e32 v164, 6, v18
	v_min_i32_e32 v18, 0x5d, v164
	v_add_u32_e32 v18, s6, v18
	v_min_i32_e32 v19, s7, v18
	v_cmp_gt_i32_e32 vcc, s4, v18
	v_mul_f32_e32 v156, 0xbfb8aa3b, v156
	v_exp_f32_e32 v167, v156
	v_cndmask_b32_e32 v18, v19, v20, vcc
	v_mad_u64_u32 v[18:19], s[8:9], v18, s62, v[16:17]
	v_lshl_add_u64 v[18:19], v[18:19], 0, v[144:145]
	v_add_co_u32_e32 v18, vcc, s74, v18
	v_and_b32_e32 v156, 0xffff0000, v168
	s_nop 0
	v_addc_co_u32_e32 v19, vcc, 0, v19, vcc
	global_load_dwordx4 v[80:83], v[18:19], off
	global_load_dwordx4 v[84:87], v[18:19], off offset:1024
	v_add_u32_e32 v18, 0x800, v108
	v_ashrrev_i32_e32 v163, 6, v18
	v_min_i32_e32 v18, 0x5d, v163
	v_add_u32_e32 v18, s6, v18
	v_min_i32_e32 v19, s7, v18
	v_cmp_gt_i32_e32 vcc, s4, v18
	v_mul_f32_e32 v156, 0xbfb8aa3b, v156
	v_exp_f32_e32 v168, v156
	v_cndmask_b32_e32 v18, v19, v20, vcc
	v_mad_u64_u32 v[18:19], s[8:9], v18, s62, v[16:17]
	v_lshl_add_u64 v[18:19], v[18:19], 0, v[144:145]
	v_add_co_u32_e32 v18, vcc, s74, v18
	v_add_f32_e32 v168, 1.0, v168
	s_nop 0
	v_addc_co_u32_e32 v19, vcc, 0, v19, vcc
	global_load_dwordx4 v[72:75], v[18:19], off
	global_load_dwordx4 v[76:79], v[18:19], off offset:1024
	v_add_u32_e32 v18, 0xa00, v108
	v_ashrrev_i32_e32 v162, 6, v18
	v_min_i32_e32 v18, 0x5d, v162
	v_add_u32_e32 v18, s6, v18
	v_min_i32_e32 v19, s7, v18
	v_cmp_gt_i32_e32 vcc, s4, v18
	v_rcp_f32_e32 v168, v168
	v_and_b32_e32 v104, 0xffff0000, v104
	v_cndmask_b32_e32 v18, v19, v20, vcc
	v_mad_u64_u32 v[18:19], s[8:9], v18, s62, v[16:17]
	v_lshl_add_u64 v[18:19], v[18:19], 0, v[144:145]
	v_add_co_u32_e32 v18, vcc, s74, v18
	v_add_f32_e32 v167, 1.0, v167
	s_nop 0
	v_addc_co_u32_e32 v19, vcc, 0, v19, vcc
	global_load_dwordx4 v[64:67], v[18:19], off
	global_load_dwordx4 v[68:71], v[18:19], off offset:1024
	v_add_u32_e32 v18, 0xc00, v108
	v_ashrrev_i32_e32 v161, 6, v18
	v_min_i32_e32 v18, 0x5d, v161
	v_add_u32_e32 v18, s6, v18
	v_min_i32_e32 v19, s7, v18
	v_cmp_gt_i32_e32 vcc, s4, v18
	v_mul_f32_e32 v104, v168, v104
	v_lshlrev_b32_e32 v168, 16, v169
	v_cndmask_b32_e32 v18, v19, v20, vcc
	v_mad_u64_u32 v[18:19], s[8:9], v18, s62, v[16:17]
	v_lshl_add_u64 v[18:19], v[18:19], 0, v[144:145]
	v_add_co_u32_e32 v18, vcc, s74, v18
	v_and_b32_e32 v169, 0xffff0000, v169
	s_nop 0
	v_addc_co_u32_e32 v19, vcc, 0, v19, vcc
	global_load_dwordx4 v[56:59], v[18:19], off
	global_load_dwordx4 v[60:63], v[18:19], off offset:1024
	v_add_u32_e32 v18, 0xe00, v108
	v_ashrrev_i32_e32 v160, 6, v18
	v_min_i32_e32 v18, 0x5d, v160
	v_add_u32_e32 v18, s6, v18
	v_min_i32_e32 v19, s7, v18
	v_cmp_gt_i32_e32 vcc, s4, v18
	v_rcp_f32_e32 v167, v167
	v_mul_f32_e32 v168, 0xbfb8aa3b, v168
	v_cndmask_b32_e32 v18, v19, v20, vcc
	v_mad_u64_u32 v[18:19], s[8:9], v18, s62, v[16:17]
	v_lshl_add_u64 v[18:19], v[18:19], 0, v[144:145]
	v_add_co_u32_e32 v18, vcc, s74, v18
	v_mul_f32_e32 v169, 0xbfb8aa3b, v169
	s_nop 0
	v_addc_co_u32_e32 v19, vcc, 0, v19, vcc
	global_load_dwordx4 v[48:51], v[18:19], off
	global_load_dwordx4 v[52:55], v[18:19], off offset:1024
	v_add_u32_e32 v18, 0x1000, v108
	v_ashrrev_i32_e32 v159, 6, v18
	v_min_i32_e32 v18, 0x5d, v159
	v_add_u32_e32 v18, s6, v18
	v_min_i32_e32 v19, s7, v18
	v_cmp_gt_i32_e32 vcc, s4, v18
	v_exp_f32_e32 v168, v168
	v_exp_f32_e32 v169, v169
	v_cndmask_b32_e32 v18, v19, v20, vcc
	v_mad_u64_u32 v[18:19], s[8:9], v18, s62, v[16:17]
	v_lshl_add_u64 v[18:19], v[18:19], 0, v[144:145]
	v_add_co_u32_e32 v18, vcc, s74, v18
	v_mul_f32_e32 v167, v167, v172
	s_nop 0
	v_addc_co_u32_e32 v19, vcc, 0, v19, vcc
	global_load_dwordx4 v[40:43], v[18:19], off
	global_load_dwordx4 v[44:47], v[18:19], off offset:1024
	v_add_u32_e32 v18, 0x1200, v108
	v_ashrrev_i32_e32 v158, 6, v18
	v_min_i32_e32 v18, 0x5d, v158
	v_add_u32_e32 v18, s6, v18
	v_min_i32_e32 v19, s7, v18
	v_cmp_gt_i32_e32 vcc, s4, v18
	v_add_u32_e32 v156, 0, v144
	s_nop 0
	v_cndmask_b32_e32 v18, v19, v20, vcc
	v_mad_u64_u32 v[18:19], s[8:9], v18, s62, v[16:17]
	v_lshl_add_u64 v[18:19], v[18:19], 0, v[144:145]
	v_add_co_u32_e32 v18, vcc, s74, v18
	s_nop 1
	v_addc_co_u32_e32 v19, vcc, 0, v19, vcc
	global_load_dwordx4 v[32:35], v[18:19], off
	global_load_dwordx4 v[36:39], v[18:19], off offset:1024
	v_add_u32_e32 v18, 0x1400, v108
	v_ashrrev_i32_e32 v157, 6, v18
	v_min_i32_e32 v18, 0x5d, v157
	v_add_u32_e32 v18, s6, v18
	v_min_i32_e32 v19, s7, v18
	v_cmp_gt_i32_e32 vcc, s4, v18
	s_nop 1
	v_cndmask_b32_e32 v18, v19, v20, vcc
	v_mad_u64_u32 v[18:19], s[8:9], v18, s62, v[16:17]
	v_lshl_add_u64 v[18:19], v[18:19], 0, v[144:145]
	v_add_co_u32_e32 v18, vcc, s74, v18
	s_nop 1
	v_addc_co_u32_e32 v19, vcc, 0, v19, vcc
	global_load_dwordx4 v[24:27], v[18:19], off
	global_load_dwordx4 v[28:31], v[18:19], off offset:1024
	v_add_u32_e32 v18, 0x1600, v108
	v_ashrrev_i32_e32 v143, 6, v18
	v_min_i32_e32 v18, 0x5d, v143
	v_add_u32_e32 v18, s6, v18
	v_min_i32_e32 v19, s7, v18
	v_cmp_gt_i32_e32 vcc, s4, v18
	s_nop 1
	v_cndmask_b32_e32 v18, v19, v20, vcc
	v_mad_u64_u32 v[16:17], s[8:9], v18, s62, v[16:17]
	v_lshl_add_u64 v[16:17], v[16:17], 0, v[144:145]
	v_add_co_u32_e32 v20, vcc, s74, v16
	s_nop 1
	v_addc_co_u32_e32 v21, vcc, 0, v17, vcc
	global_load_dwordx4 v[16:19], v[20:21], off
	s_nop 0
	global_load_dwordx4 v[20:23], v[20:21], off offset:1024
	v_cvt_pk_bf16_f32 v104, v167, v104
	v_add_f32_e32 v167, 1.0, v168
	v_add_f32_e32 v168, 1.0, v169
	v_rcp_f32_e32 v167, v167
	v_rcp_f32_e32 v168, v168
	v_lshlrev_b32_e32 v169, 16, v105
	v_and_b32_e32 v105, 0xffff0000, v105
	v_mul_f32_e32 v167, v167, v169
	v_mul_f32_e32 v105, v168, v105
	v_lshlrev_b32_e32 v168, 16, v170
	v_and_b32_e32 v169, 0xffff0000, v170
	v_mul_f32_e32 v168, 0xbfb8aa3b, v168
	v_mul_f32_e32 v169, 0xbfb8aa3b, v169
	v_exp_f32_e32 v168, v168
	v_exp_f32_e32 v169, v169
	v_cvt_pk_bf16_f32 v105, v167, v105
	v_cmp_gt_i32_e32 vcc, s88, v142
	v_add_f32_e32 v167, 1.0, v168
	v_add_f32_e32 v168, 1.0, v169
	v_rcp_f32_e32 v167, v167
	v_rcp_f32_e32 v168, v168
	v_lshlrev_b32_e32 v169, 16, v106
	v_and_b32_e32 v106, 0xffff0000, v106
	v_mul_f32_e32 v167, v167, v169
	v_mul_f32_e32 v106, v168, v106
	v_lshlrev_b32_e32 v168, 16, v171
	v_and_b32_e32 v169, 0xffff0000, v171
	v_mul_f32_e32 v168, 0xbfb8aa3b, v168
	v_mul_f32_e32 v169, 0xbfb8aa3b, v169
	v_exp_f32_e32 v168, v168
	v_exp_f32_e32 v169, v169
	v_cvt_pk_bf16_f32 v106, v167, v106
	v_add_f32_e32 v167, 1.0, v168
	v_add_f32_e32 v168, 1.0, v169
	v_rcp_f32_e32 v168, v168
	v_rcp_f32_e32 v167, v167
	v_lshlrev_b32_e32 v169, 16, v107
	v_and_b32_e32 v107, 0xffff0000, v107
	v_mul_f32_e32 v107, v168, v107
	v_mul_f32_e32 v167, v167, v169
	v_cvt_pk_bf16_f32 v107, v167, v107
	s_and_saveexec_b64 s[76:77], vcc
	s_cbranch_execz .LBB0_372
	v_add_u32_e32 v167, s6, v142
	v_cmp_le_i32_e32 vcc, s4, v167
	v_cmp_gt_i32_e64 s[42:43], s5, v167
	s_and_b64 vcc, vcc, s[42:43]
	v_cndmask_b32_e32 v104, 0, v104, vcc
	v_cndmask_b32_e32 v105, 0, v105, vcc
	v_cndmask_b32_e32 v106, 0, v106, vcc
	v_cndmask_b32_e32 v107, 0, v107, vcc
	v_lshl_add_u32 v167, v142, 10, v156
	ds_write_b128 v167, v[104:107]
